# LRU gates: bias add and log2e scaling folded into fma / pre-scaled per-lane constants (48 fewer VALU per unit-wave)
# baseline (speedup 1.0000x reference)
; __device__ __forceinline__ float fast_sigmoid(float v) { return __builtin_amdgcn_rcpf(1.0f + __builtin_amdgcn_exp2f(-1.44269504089f * v)); }
; #define LAS __attribute__((address_space(3)))
; __device__ __forceinline__ void lru_phase(LAS unsigned char* lds, const bf16* XB, const bf16* Y, bf16* HY, const bf16* WRt, const bf16* WIt,
;         const float* convw, const float* convb, const float* br, const float* bi, const float* lam, unsigned long long* gran, int G, int bid, int wave_s) {
;     ...
;             f32x16 pr, pi;
; #pragma unroll
;             for (int i = 0; i < 16; ++i) { pr[i] = 0.f; pi[i] = 0.f; }
;             const int trow = 32 * rb + 16 * ((ql >> 2) & 1) + 4 * (ql >> 3) + (ql & 3);
; #pragma unroll
;             for (int s = 0; s < 4; ++s) {
;                 const bf16x8 af = *(const LAS bf16x8*)(xcB + trow * KP + 16 * s + 8 * hi);
;                 const bf16x8 wr_ = *(const LAS bf16x8*)(wL + d * KP + 16 * s + 8 * hi), wi_ = *(const LAS bf16x8*)(wL + (64 + d) * KP + 16 * s + 8 * hi);
;                 pr = __builtin_amdgcn_mfma_f32_32x32x16_bf16(af, wr_, pr, 0, 0, 0);
;                 pi = __builtin_amdgcn_mfma_f32_32x32x16_bf16(af, wi_, pi, 0, 0, 0);
;             }
;             const float brv = parL[320 + d], biv = parL[384 + d], ls8 = parL[448 + d];
;             float A = 1.f, H = 0.f;
; #pragma unroll
;             for (int i = 0; i < 16; ++i) {
;                 const float r = pg8::fast_sigmoid(pr[i] + brv), ig = pg8::fast_sigmoid(pi[i] + biv);
;                 const float la = ls8 * r;
;                 const float a = __builtin_amdgcn_exp2f(la * LOG2E);
;                 const float mult = __builtin_amdgcn_sqrtf(fmaxf(1.0f - a * a, 0.f));
;                 const float u = mult * ig * xcF[(tb + i) * 64 + d];
;                 av[i] = a; uv[i] = u; H = a * H + u; A *= a;
.LBB0_2144:
	ds_read_b128 v[0:3], v107
	ds_read_b128 v[4:7], v108 offset:32768
	ds_read_b128 v[208:211], v107 offset:32
	ds_read_b128 v[212:215], v108 offset:32800
	v_add_u32_e32 v86, v111, v119
	s_cmp_gt_i32 s94, 14
	s_waitcnt lgkmcnt(2)
	v_mfma_f32_32x32x16_bf16 v[16:31], v[0:3], v[4:7], 0
	ds_read_b128 v[4:7], v108 offset:41984
	ds_read_b128 v[216:219], v108 offset:42016
	s_cselect_b64 s[6:7], -1, 0
	s_or_b64 s[6:7], s[56:57], s[6:7]
	s_and_b64 vcc, exec, s[6:7]
	s_waitcnt lgkmcnt(1)
	v_mfma_f32_32x32x16_bf16 v[0:15], v[0:3], v[4:7], 0
	v_mfma_f32_32x32x16_bf16 v[16:31], v[208:211], v[212:215], v[16:31]
	s_waitcnt lgkmcnt(0)
	v_mfma_f32_32x32x16_bf16 v[0:15], v[208:211], v[216:219], v[0:15]
	ds_read_b128 v[208:211], v107 offset:64
	ds_read_b128 v[212:215], v108 offset:32832
	ds_read_b128 v[216:219], v107 offset:96
	ds_read_b128 v[220:223], v108 offset:32864
	s_waitcnt lgkmcnt(2)
	v_mfma_f32_32x32x16_bf16 v[16:31], v[208:211], v[212:215], v[16:31]
	ds_read_b128 v[212:215], v108 offset:42048
	ds_read_b128 v[224:227], v108 offset:42080
	ds_read2st64_b32 v[98:99], v110 offset0:5 offset1:6
	ds_read_b32 v65, v110 offset:1792
	ds_read_b32 v86, v86
	ds_read_b32 v91, v191
	ds_read_b32 v93, v192
	ds_read_b32 v97, v193
	ds_read_b32 v174, v194
	ds_read_b32 v228, v195
	s_waitcnt lgkmcnt(10)
	v_mfma_f32_32x32x16_bf16 v[16:31], v[216:219], v[220:223], v[16:31]
	s_waitcnt lgkmcnt(9)
	v_mfma_f32_32x32x16_bf16 v[0:15], v[208:211], v[212:215], v[0:15]
	s_waitcnt lgkmcnt(7)
	s_mov_b32 s98, 0xbfb8aa3b
	v_mul_f32_e32 v98, 0xbfb8aa3b, v98
	v_mul_f32_e32 v99, 0xbfb8aa3b, v99
	s_nop 6
	v_fma_f32 v16, v16, s98, v98
	v_exp_f32_e32 v16, v16
	v_fma_f32 v18, v18, s98, v98
	v_exp_f32_e32 v18, v18
	v_add_f32_e32 v16, 1.0, v16
	v_rcp_f32_e32 v16, v16
	v_mfma_f32_32x32x16_bf16 v[0:15], v[216:219], v[224:227], v[0:15]
	s_waitcnt lgkmcnt(6)
	v_mul_f32_e32 v65, 0x3fb8aa3b, v65
	v_mul_f32_e32 v16, v65, v16
	v_exp_f32_e32 v207, v16
	v_fma_f32 v16, v17, s98, v98
	v_exp_f32_e32 v16, v16
	s_nop 5
	v_fma_f32 v0, v0, s98, v99
	v_exp_f32_e32 v0, v0
	v_add_f32_e32 v16, 1.0, v16
	v_rcp_f32_e32 v16, v16
	v_fma_f32 v17, -v207, v207, 1.0
	v_add_f32_e32 v0, 1.0, v0
	v_max_f32_e32 v17, 0, v17
	v_mul_f32_e32 v16, v65, v16
	v_rcp_f32_e32 v0, v0
	v_exp_f32_e32 v208, v16
	v_sqrt_f32_e32 v16, v17
	v_fma_f32 v1, v1, s98, v99
	v_exp_f32_e32 v1, v1
	v_mul_f32_e32 v0, v0, v16
	v_add_f32_e32 v16, 1.0, v18
	v_rcp_f32_e32 v16, v16
	v_fma_f32 v17, -v208, v208, 1.0
	v_add_f32_e32 v1, 1.0, v1
	v_max_f32_e32 v17, 0, v17
	v_fma_f32 v2, v2, s98, v99
	v_mul_f32_e32 v16, v65, v16
	v_rcp_f32_e32 v1, v1
	v_sqrt_f32_e32 v17, v17
	v_exp_f32_e32 v2, v2
	v_exp_f32_e32 v210, v16
	v_mul_f32_e32 v1, v1, v17
	s_waitcnt lgkmcnt(4)
	v_mul_f32_e32 v211, v91, v1
	v_add_f32_e32 v1, 1.0, v2
	v_fma_f32 v2, -v210, v210, 1.0
	v_fma_f32 v16, v19, s98, v98
	v_max_f32_e32 v2, 0, v2
	v_rcp_f32_e32 v1, v1
	v_sqrt_f32_e32 v2, v2
	v_exp_f32_e32 v16, v16
	v_fma_f32 v3, v3, s98, v99
	v_mul_f32_e32 v1, v1, v2
	v_add_f32_e32 v2, 1.0, v16
	v_rcp_f32_e32 v2, v2
	v_exp_f32_e32 v3, v3
	s_waitcnt lgkmcnt(3)
	v_mul_f32_e32 v213, v93, v1
	v_mul_f32_e32 v17, v207, v208
	v_mul_f32_e32 v2, v65, v2
	v_exp_f32_e32 v212, v2
	v_add_f32_e32 v1, 1.0, v3
	v_fma_f32 v3, v20, s98, v98
	v_fma_f32 v2, -v212, v212, 1.0
	v_max_f32_e32 v2, 0, v2
	v_rcp_f32_e32 v1, v1
	v_sqrt_f32_e32 v2, v2
	v_exp_f32_e32 v3, v3
	v_mul_f32_e32 v16, v210, v17
	v_mul_f32_e32 v209, v86, v0
	v_mul_f32_e32 v1, v1, v2
	v_add_f32_e32 v2, 1.0, v3
	v_rcp_f32_e32 v2, v2
	v_fma_f32 v3, v4, s98, v99
	v_exp_f32_e32 v3, v3
	v_mul_f32_e32 v2, v65, v2
	v_exp_f32_e32 v214, v2
	s_waitcnt lgkmcnt(2)
	v_mul_f32_e32 v215, v97, v1
	v_add_f32_e32 v1, 1.0, v3
	v_fma_f32 v3, v21, s98, v98
	v_fma_f32 v2, -v214, v214, 1.0
	v_max_f32_e32 v2, 0, v2
	v_rcp_f32_e32 v1, v1
	v_sqrt_f32_e32 v2, v2
	v_exp_f32_e32 v3, v3
	v_mul_f32_e32 v4, v212, v16
	v_fma_f32 v0, 0, v207, v209
	v_mul_f32_e32 v1, v1, v2
	v_add_f32_e32 v2, 1.0, v3
	v_rcp_f32_e32 v2, v2
	v_fma_f32 v3, v5, s98, v99
	v_exp_f32_e32 v3, v3
	v_mul_f32_e32 v2, v65, v2
	v_exp_f32_e32 v216, v2
	s_waitcnt lgkmcnt(1)
	v_mul_f32_e32 v217, v174, v1
	v_add_f32_e32 v1, 1.0, v3
	v_fma_f32 v3, v22, s98, v98
	v_fma_f32 v2, -v216, v216, 1.0
	v_max_f32_e32 v2, 0, v2
	v_rcp_f32_e32 v1, v1
	v_sqrt_f32_e32 v2, v2
	v_exp_f32_e32 v3, v3
	v_fma_f32 v0, v208, v0, v211
	v_fma_f32 v0, v210, v0, v213
	v_mul_f32_e32 v1, v1, v2
	v_add_f32_e32 v2, 1.0, v3
	v_rcp_f32_e32 v2, v2
	v_fma_f32 v3, v6, s98, v99
	v_exp_f32_e32 v3, v3
	v_mul_f32_e32 v2, v65, v2
	v_exp_f32_e32 v218, v2
	s_waitcnt lgkmcnt(0)
; __device__ __forceinline__ float fast_sigmoid(float v) { return __builtin_amdgcn_rcpf(1.0f + __builtin_amdgcn_exp2f(-1.44269504089f * v)); }
; #define LDS_BARRIER() do { asm volatile("s_waitcnt lgkmcnt(0)" ::: "memory"); __builtin_amdgcn_s_barrier(); asm volatile("" ::: "memory"); } while (0)
; __device__ __forceinline__ void lru_phase(LAS unsigned char* lds, const bf16* XB, const bf16* Y, bf16* HY, const bf16* WRt, const bf16* WIt,
;         const float* convw, const float* convb, const float* br, const float* bi, const float* lam, unsigned long long* gran, int G, int bid, int wave_s) {
;     ...
;             for (int i = 0; i < 16; ++i) {
;                 const float r = pg8::fast_sigmoid(pr[i] + brv), ig = pg8::fast_sigmoid(pi[i] + biv);
;                 const float la = ls8 * r;
;                 const float a = __builtin_amdgcn_exp2f(la * LOG2E);
;                 const float mult = __builtin_amdgcn_sqrtf(fmaxf(1.0f - a * a, 0.f));
;                 const float u = mult * ig * xcF[(tb + i) * 64 + d];
;                 av[i] = a; uv[i] = u; H = a * H + u; A *= a;
;             }
;             segA[sg * 64 + d] = A; segH[sg * 64 + d] = H;
;         }
;         LDS_BARRIER();
	v_mul_f32_e32 v219, v228, v1
	v_add_f32_e32 v1, 1.0, v3
	v_fma_f32 v3, v23, s98, v98
	v_fma_f32 v2, -v218, v218, 1.0
	v_max_f32_e32 v2, 0, v2
	v_rcp_f32_e32 v1, v1
	v_sqrt_f32_e32 v2, v2
	v_exp_f32_e32 v3, v3
	v_fma_f32 v0, v212, v0, v215
	v_mul_f32_e32 v4, v214, v4
	v_mul_f32_e32 v1, v1, v2
	v_add_f32_e32 v2, 1.0, v3
	v_rcp_f32_e32 v2, v2
	v_fma_f32 v3, v7, s98, v99
	v_exp_f32_e32 v3, v3
	v_mul_f32_e32 v2, v65, v2
	v_exp_f32_e32 v220, v2
	ds_read_b32 v2, v196
	ds_read_b32 v5, v197
	ds_read_b32 v6, v198
	ds_read_b32 v7, v199
	ds_read_b32 v16, v200
	ds_read_b32 v17, v201
	ds_read_b32 v18, v202
	ds_read_b32 v19, v203
	s_waitcnt lgkmcnt(7)
	v_mul_f32_e32 v221, v2, v1
	v_add_f32_e32 v1, 1.0, v3
	v_fma_f32 v2, -v220, v220, 1.0
	v_fma_f32 v3, v24, s98, v98
	v_max_f32_e32 v2, 0, v2
	v_rcp_f32_e32 v1, v1
	v_sqrt_f32_e32 v2, v2
	v_exp_f32_e32 v3, v3
	v_fma_f32 v0, v214, v0, v217
	v_mul_f32_e32 v4, v216, v4
	v_mul_f32_e32 v1, v1, v2
	v_add_f32_e32 v2, 1.0, v3
	v_rcp_f32_e32 v2, v2
	v_fma_f32 v3, v8, s98, v99
	v_exp_f32_e32 v3, v3
	v_mul_f32_e32 v2, v65, v2
	v_exp_f32_e32 v225, v2
	s_waitcnt lgkmcnt(6)
	v_mul_f32_e32 v227, v5, v1
	v_add_f32_e32 v1, 1.0, v3
	v_fma_f32 v3, v25, s98, v98
	v_fma_f32 v2, -v225, v225, 1.0
	v_max_f32_e32 v2, 0, v2
	v_rcp_f32_e32 v1, v1
	v_sqrt_f32_e32 v2, v2
	v_exp_f32_e32 v3, v3
	v_fma_f32 v0, v216, v0, v219
	v_mul_f32_e32 v4, v218, v4
	v_mul_f32_e32 v1, v1, v2
	v_add_f32_e32 v2, 1.0, v3
	v_rcp_f32_e32 v2, v2
	v_fma_f32 v3, v9, s98, v99
	v_exp_f32_e32 v3, v3
	v_mul_f32_e32 v2, v65, v2
	v_exp_f32_e32 v230, v2
	s_waitcnt lgkmcnt(5)
	v_mul_f32_e32 v231, v6, v1
	v_add_f32_e32 v1, 1.0, v3
	v_fma_f32 v3, v26, s98, v98
	v_fma_f32 v2, -v230, v230, 1.0
	v_max_f32_e32 v2, 0, v2
	v_rcp_f32_e32 v1, v1
	v_sqrt_f32_e32 v2, v2
	v_exp_f32_e32 v3, v3
	v_fma_f32 v0, v218, v0, v221
	v_mul_f32_e32 v4, v220, v4
	v_mul_f32_e32 v1, v1, v2
	v_add_f32_e32 v2, 1.0, v3
	v_rcp_f32_e32 v2, v2
	v_fma_f32 v3, v10, s98, v99
	v_exp_f32_e32 v3, v3
	v_mul_f32_e32 v2, v65, v2
	v_exp_f32_e32 v233, v2
	s_waitcnt lgkmcnt(4)
	v_mul_f32_e32 v234, v7, v1
	v_add_f32_e32 v1, 1.0, v3
	v_fma_f32 v3, v27, s98, v98
	v_fma_f32 v2, -v233, v233, 1.0
	v_max_f32_e32 v2, 0, v2
	v_rcp_f32_e32 v1, v1
	v_sqrt_f32_e32 v2, v2
	v_exp_f32_e32 v3, v3
	v_fma_f32 v0, v220, v0, v227
	v_mul_f32_e32 v4, v225, v4
	v_mul_f32_e32 v1, v1, v2
	v_add_f32_e32 v2, 1.0, v3
	v_rcp_f32_e32 v2, v2
	v_fma_f32 v3, v11, s98, v99
	v_exp_f32_e32 v3, v3
	v_mul_f32_e32 v2, v65, v2
	v_exp_f32_e32 v224, v2
	s_waitcnt lgkmcnt(3)
	v_mul_f32_e32 v226, v1, v16
	v_add_f32_e32 v1, 1.0, v3
	v_fma_f32 v3, v28, s98, v98
	v_fma_f32 v2, -v224, v224, 1.0
	v_max_f32_e32 v2, 0, v2
	v_rcp_f32_e32 v1, v1
	v_sqrt_f32_e32 v2, v2
	v_exp_f32_e32 v3, v3
	v_fma_f32 v0, v225, v0, v231
	v_mul_f32_e32 v4, v230, v4
	v_mul_f32_e32 v1, v1, v2
	v_add_f32_e32 v2, 1.0, v3
	v_rcp_f32_e32 v2, v2
	v_fma_f32 v3, v12, s98, v99
	v_exp_f32_e32 v3, v3
	v_mul_f32_e32 v2, v65, v2
	v_exp_f32_e32 v222, v2
	s_waitcnt lgkmcnt(2)
	v_mul_f32_e32 v223, v1, v17
	v_add_f32_e32 v1, 1.0, v3
	v_fma_f32 v3, v29, s98, v98
	v_fma_f32 v2, -v222, v222, 1.0
	v_max_f32_e32 v2, 0, v2
	v_rcp_f32_e32 v1, v1
	v_sqrt_f32_e32 v2, v2
	v_exp_f32_e32 v3, v3
	v_fma_f32 v0, v230, v0, v234
	v_mul_f32_e32 v4, v233, v4
	v_mul_f32_e32 v1, v1, v2
	v_add_f32_e32 v2, 1.0, v3
	v_rcp_f32_e32 v2, v2
	v_fma_f32 v3, v13, s98, v99
	v_exp_f32_e32 v3, v3
	v_mul_f32_e32 v2, v65, v2
	v_exp_f32_e32 v228, v2
	s_waitcnt lgkmcnt(1)
	v_mul_f32_e32 v229, v1, v18
	v_add_f32_e32 v1, 1.0, v3
	v_fma_f32 v3, v30, s98, v98
	v_fma_f32 v2, -v228, v228, 1.0
	v_max_f32_e32 v2, 0, v2
	v_rcp_f32_e32 v1, v1
	v_sqrt_f32_e32 v2, v2
	v_exp_f32_e32 v3, v3
	ds_read_b32 v6, v205
	v_fma_f32 v0, v233, v0, v226
	v_mul_f32_e32 v1, v1, v2
	v_add_f32_e32 v2, 1.0, v3
	v_rcp_f32_e32 v2, v2
	v_fma_f32 v3, v14, s98, v99
	v_exp_f32_e32 v3, v3
	v_mul_f32_e32 v2, v65, v2
	v_exp_f32_e32 v30, v2
	s_waitcnt lgkmcnt(1)
	v_mul_f32_e32 v232, v1, v19
	v_add_f32_e32 v1, 1.0, v3
	v_fma_f32 v3, v31, s98, v98
	v_fma_f32 v2, -v30, v30, 1.0
	v_max_f32_e32 v2, 0, v2
	v_rcp_f32_e32 v1, v1
	v_sqrt_f32_e32 v2, v2
	v_exp_f32_e32 v3, v3
	v_mul_f32_e32 v4, v224, v4
	v_fma_f32 v0, v224, v0, v223
	v_mul_f32_e32 v1, v1, v2
	v_add_f32_e32 v2, 1.0, v3
	v_rcp_f32_e32 v2, v2
	v_fma_f32 v3, v15, s98, v99
	v_exp_f32_e32 v3, v3
	v_mul_f32_e32 v2, v65, v2
	v_exp_f32_e32 v31, v2
	ds_read_b32 v2, v204
	v_add_f32_e32 v3, 1.0, v3
	v_rcp_f32_e32 v3, v3
	v_fma_f32 v5, -v31, v31, 1.0
	v_max_f32_e32 v5, 0, v5
	v_sqrt_f32_e32 v5, v5
	v_mul_f32_e32 v4, v222, v4
	v_fma_f32 v0, v222, v0, v229
	v_mul_f32_e32 v4, v228, v4
	v_fma_f32 v0, v228, v0, v232
	s_waitcnt lgkmcnt(0)
	v_mul_f32_e32 v98, v1, v2
	v_mul_f32_e32 v1, v30, v4
	v_mul_f32_e32 v2, v3, v5
	v_fma_f32 v0, v30, v0, v98
	v_mul_f32_e32 v99, v2, v6
	v_mul_f32_e32 v1, v31, v1
	v_fma_f32 v0, v31, v0, v99
	ds_write_b32 v112, v1
	ds_write_b32 v113, v0
	s_waitcnt lgkmcnt(0)
	s_barrier
	s_cbranch_vccz .LBB0_2147
	s_andn2_b64 vcc, exec, s[62:63]
	s_cbranch_vccz .LBB0_2148
